# v71 plus DA map prologue prefetches 4 key tiles instead of 2 before the first barrier
# speedup vs baseline: 1.0032x; 1.0024x over previous
; __device__ __forceinline__ void flash_da2(LAS unsigned char* lds, const bf16* __restrict__ Qw, const bf16* __restrict__ Kb, const bf16* __restrict__ VTb,
;                                           int NT, int qpos_w, f32x16 (&o)[4], float& mref, float& lsum) {
;     ...
;     bf16x8 qf[4];
; #pragma unroll
;     for (int d0 = 0; d0 < 4; ++d0) qf[d0] = *(const bf16x8*)(Qw + (size_t)r32 * 64 + d0 * 16 + hi * 8);
;     const int lrow = wid * 8 + (lane >> 3), pch = lane & 7, lch = pch ^ ((lrow >> 1) & 7);
;     const int rho = lrow & 31, key = (lrow & 32) + 16 * ((rho >> 2) & 1) + 4 * (rho >> 3) + (rho & 3);
;     const bf16* ksrc = Kb + key * 64 + lch * 8;
;     const bf16* vsrc = VTb + lrow * 64 + lch * 8;
;     const unsigned kdst = lds0 + A_K + wid * 1024, vdst = lds0 + A_V + wid * 1024;
;     const int sw = (r32 >> 1) & 7;
;     unsigned kaddr[4], vaddr[4];
; #pragma unroll
;     for (int d0 = 0; d0 < 4; ++d0) kaddr[d0] = A_K + r32 * 128 + (((2 * d0 + hi) ^ sw) << 4);
; #pragma unroll
;     for (int c4 = 0; c4 < 4; ++c4) vaddr[c4] = A_V + r32 * 128 + (((4 * (c4 >> 1) + 2 * hi + (c4 & 1)) ^ sw) << 4);
; #pragma unroll
;     for (int j = 0; j < 2; ++j) {
;         glds16(ksrc + (size_t)j * 4096, (unsigned)__builtin_amdgcn_readfirstlane(kdst + j * 8192));
;         glds16(vsrc + (size_t)j * 8192, (unsigned)__builtin_amdgcn_readfirstlane(vdst + j * 16384));
;         glds16(vsrc + (size_t)j * 8192 + 4096, (unsigned)__builtin_amdgcn_readfirstlane(vdst + j * 16384 + 8192));
;     }
;     asm volatile("" :: "v"(qf[0]), "v"(qf[1]), "v"(qf[2]), "v"(qf[3]));
;     asm volatile("s_waitcnt vmcnt(0) lgkmcnt(0)\n\ts_barrier" ::: "memory");
.LBB0_426:
	s_mul_i32 s8, s51, s8
	s_xor_b64 s[58:59], s[10:11], -1
	s_lshl_b64 s[10:11], s[8:9], 1
	v_lshl_add_u64 v[2:3], v[158:159], 0, s[10:11]
	global_load_dwordx4 v[112:115], v[2:3], off
	global_load_dwordx4 v[116:119], v[2:3], off offset:32
	global_load_dwordx4 v[120:123], v[2:3], off offset:64
	global_load_dwordx4 v[124:127], v[2:3], off offset:96
	s_add_u32 s52, s88, s10
	v_readfirstlane_b32 s35, v151
	s_addc_u32 s53, s89, s11
	s_lshr_b32 s10, s35, 6
	s_lshl_b32 s11, s10, 3
	s_lshr_b32 s35, s35, 4
	v_or_b32_e32 v0, s11, v195
	s_and_b32 s11, s11, 32
	s_and_b32 s35, s35, 12
	s_or_b32 s11, s11, s35
	v_lshrrev_b32_e32 v8, 1, v0
	v_or_b32_e32 v4, s11, v196
	v_lshlrev_b32_e32 v0, 7, v0
	v_xor_b32_e32 v6, v8, v151
	v_lshl_add_u64 v[2:3], s[54:55], 0, v[0:1]
	v_lshlrev_b32_e32 v0, 7, v4
	v_lshl_add_u64 v[4:5], s[52:53], 0, v[0:1]
	v_lshlrev_b32_e32 v0, 4, v6
	s_lshl_b32 s11, s10, 10
	v_and_b32_e32 v0, 0x70, v0
	s_add_i32 s35, s11, 0
	v_lshl_add_u64 v[4:5], v[4:5], 0, v[0:1]
	s_mov_b32 s11, m0
	s_mov_b32 m0, s35
	s_nop 0
	global_load_lds_dwordx4 v[4:5], off
	s_mov_b32 m0, s11
	v_lshl_add_u64 v[2:3], v[2:3], 0, v[0:1]
	s_add_i32 s52, s35, 0x8000
	s_mov_b32 s11, m0
	s_mov_b32 m0, s52
	s_nop 0
	global_load_lds_dwordx4 v[2:3], off
	s_mov_b32 m0, s11
	v_lshl_add_u64 v[6:7], v[2:3], 0, s[38:39]
	s_add_i32 s11, s52, 0x2000
	s_mov_b32 s53, m0
	s_mov_b32 m0, s11
	s_nop 0
	global_load_lds_dwordx4 v[6:7], off
	s_mov_b32 m0, s53
	v_lshl_add_u64 v[6:7], v[4:5], 0, s[38:39]
	s_add_i32 s11, s35, 0x2000
	s_mov_b32 s53, m0
	s_mov_b32 m0, s11
	s_nop 0
	global_load_lds_dwordx4 v[6:7], off
	s_mov_b32 m0, s53
	v_lshl_add_u64 v[6:7], v[2:3], 0, s[40:41]
	s_add_i32 s11, s35, 0xc000
	s_mov_b32 s53, m0
	s_mov_b32 m0, s11
	s_nop 0
	global_load_lds_dwordx4 v[6:7], off
	s_mov_b32 m0, s53
	v_lshl_add_u64 v[2:3], v[2:3], 0, s[42:43]
	v_bitop3_b32 v0, v8, 7, v151 bitop3:0x48
	s_add_i32 s11, s35, 0xe000
	s_mov_b32 s53, m0
	s_mov_b32 m0, s11
	s_nop 0
	global_load_lds_dwordx4 v[2:3], off
	s_mov_b32 m0, s53
	s_mov_b32 s99, m0
	s_mov_b64 s[100:101], 0x8000
	v_lshl_add_u64 v[6:7], v[4:5], 0, s[40:41]
	s_add_i32 m0, s35, 0x4000
	s_nop 0
	global_load_lds_dwordx4 v[6:7], off
	v_lshl_add_u64 v[6:7], v[2:3], 0, s[38:39]
	s_add_i32 m0, s35, 0x10000
	s_nop 0
	global_load_lds_dwordx4 v[6:7], off
	v_lshl_add_u64 v[6:7], v[2:3], 0, s[40:41]
	s_add_i32 m0, s35, 0x12000
	s_nop 0
	global_load_lds_dwordx4 v[6:7], off
	v_lshl_add_u64 v[6:7], v[4:5], 0, s[42:43]
	s_add_i32 m0, s35, 0x6000
	s_nop 0
	global_load_lds_dwordx4 v[6:7], off
	v_lshl_add_u64 v[6:7], v[2:3], 0, s[42:43]
	s_add_i32 m0, s35, 0x14000
	s_nop 0
	global_load_lds_dwordx4 v[6:7], off
	v_lshl_add_u64 v[6:7], v[2:3], 0, s[100:101]
	s_add_i32 m0, s35, 0x16000
	s_nop 0
	global_load_lds_dwordx4 v[6:7], off
	s_mov_b32 m0, s99
	v_lshlrev_b32_e32 v0, 4, v0
	v_lshl_or_b32 v2, s10, 9, v216
	v_mov_b32_e32 v3, v1
	v_lshl_add_u64 v[2:3], v[2:3], 1, v[0:1]
	v_mov_b32_e32 v14, v1
	v_mov_b32_e32 v15, v1
	v_lshl_add_u64 v[160:161], s[56:57], 0, v[2:3]
	v_lshl_add_u64 v[162:163], v[4:5], 0, s[42:43]
	v_mov_b32_e32 v0, v1
	v_mov_b32_e32 v2, v1
	v_mov_b32_e32 v3, v1
	v_mov_b32_e32 v4, v1
	v_mov_b32_e32 v5, v1
	v_mov_b32_e32 v6, v1
	v_mov_b32_e32 v7, v1
	v_mov_b32_e32 v8, v1
	v_mov_b32_e32 v9, v1
	v_mov_b32_e32 v10, v1
	v_mov_b32_e32 v11, v1
	v_mov_b32_e32 v12, v1
	v_mov_b32_e32 v13, v1
	v_mov_b64_e32 v[30:31], v[14:15]
	v_mov_b64_e32 v[46:47], v[14:15]
	v_mov_b64_e32 v[62:63], v[14:15]
	v_mov_b64_e32 v[78:79], v[14:15]
	s_mov_b32 s8, 3
	s_mov_b32 s53, s91
	v_mov_b32_e32 v223, v221
	v_mov_b64_e32 v[28:29], v[12:13]
	v_mov_b64_e32 v[26:27], v[10:11]
	v_mov_b64_e32 v[24:25], v[8:9]
	v_mov_b64_e32 v[22:23], v[6:7]
	v_mov_b64_e32 v[20:21], v[4:5]
	v_mov_b64_e32 v[18:19], v[2:3]
	v_mov_b64_e32 v[16:17], v[0:1]
	v_mov_b64_e32 v[44:45], v[12:13]
	v_mov_b64_e32 v[42:43], v[10:11]
	v_mov_b64_e32 v[40:41], v[8:9]
	v_mov_b64_e32 v[38:39], v[6:7]
	s_waitcnt vmcnt(6)
	s_waitcnt vmcnt(6) lgkmcnt(0)
	s_barrier
	v_mov_b64_e32 v[36:37], v[4:5]
	v_mov_b64_e32 v[34:35], v[2:3]
	v_mov_b64_e32 v[32:33], v[0:1]
	v_mov_b64_e32 v[60:61], v[12:13]
	v_mov_b64_e32 v[58:59], v[10:11]
	v_mov_b64_e32 v[56:57], v[8:9]
	v_mov_b64_e32 v[54:55], v[6:7]
	v_mov_b64_e32 v[52:53], v[4:5]
	v_mov_b64_e32 v[50:51], v[2:3]
	v_mov_b64_e32 v[48:49], v[0:1]
	v_mov_b64_e32 v[76:77], v[12:13]
	v_mov_b64_e32 v[74:75], v[10:11]
	v_mov_b64_e32 v[72:73], v[8:9]
	v_mov_b64_e32 v[70:71], v[6:7]
	v_mov_b64_e32 v[68:69], v[4:5]
	v_mov_b64_e32 v[66:67], v[2:3]
	v_mov_b64_e32 v[64:65], v[0:1]
	v_mov_b32_e32 v224, 0
	v_mov_b32_e32 v0, 0
	v_mov_b32_e32 v225, 0
	s_mov_b32 s10, 0
	s_branch .LBB0_428

; template <bool ISSUE> ...
;     ...
;     if (ISSUE) {
;         if (t + 2 < NT) {
;             glds16(ksrc + (size_t)(t + 2) * 4096, (unsigned)__builtin_amdgcn_readfirstlane(kdst + ((t + 2) & 3) * 8192));
;             glds16(vsrc + (size_t)(t + 2) * 8192, (unsigned)__builtin_amdgcn_readfirstlane(vdst + ((t + 2) & 3) * 16384));
;             glds16(vsrc + (size_t)(t + 2) * 8192 + 4096, (unsigned)__builtin_amdgcn_readfirstlane(vdst + ((t + 2) & 3) * 16384 + 8192));
;             glds16(ksrc + (size_t)(t + 3) * 4096, (unsigned)__builtin_amdgcn_readfirstlane(kdst + ((t + 3) & 3) * 8192));
;             glds16(vsrc + (size_t)(t + 3) * 8192, (unsigned)__builtin_amdgcn_readfirstlane(vdst + ((t + 3) & 3) * 16384));
;             glds16(vsrc + (size_t)(t + 3) * 8192 + 4096, (unsigned)__builtin_amdgcn_readfirstlane(vdst + ((t + 3) & 3) * 16384 + 8192));
;         }
;     }
.LBB0_438:
	s_add_i32 s66, s8, -1
	s_cmp_eq_u32 s8, 3
	s_cbranch_scc1 .LBB0_440
	s_cmp_ge_u32 s66, s90
	s_cbranch_scc1 .LBB0_440
	s_and_b32 s11, s66, 2
	s_lshl_b32 s62, s11, 13
	v_lshl_add_u64 v[14:15], v[162:163], 0, s[44:45]
	s_add_i32 s62, s62, s35
	s_mov_b32 s63, m0
	s_mov_b32 m0, s62
	s_nop 0
	global_load_lds_dwordx4 v[14:15], off
	s_mov_b32 m0, s63
	s_movk_i32 s62, 0xc000
	s_lshl_b32 s11, s11, 14
	s_mov_b32 s63, -1
	s_add_i32 s11, s11, s52
	v_lshl_add_u64 v[14:15], v[160:161], 0, s[62:63]
	s_mov_b32 s62, m0
	s_mov_b32 m0, s11
	s_nop 0
	global_load_lds_dwordx4 v[14:15], off
	s_mov_b32 m0, s62
	s_addk_i32 s11, 0x2000
	v_lshl_add_u64 v[14:15], v[160:161], 0, s[44:45]
	s_mov_b32 s62, m0
	s_mov_b32 m0, s11
	s_nop 0
	global_load_lds_dwordx4 v[14:15], off
	s_mov_b32 m0, s62
	s_and_b32 s11, s8, 3
	s_lshl_b32 s62, s11, 13
	s_add_i32 s62, s62, s35
	s_mov_b32 s63, m0
	s_mov_b32 m0, s62
	s_nop 0
	global_load_lds_dwordx4 v[162:163], off
	s_mov_b32 m0, s63
	s_lshl_b32 s11, s11, 14
	s_add_i32 s11, s11, s52
	s_mov_b32 s62, m0
	s_mov_b32 m0, s11
	s_nop 0
	global_load_lds_dwordx4 v[160:161], off
	s_mov_b32 m0, s62
	v_lshl_add_u64 v[14:15], v[160:161], 0, s[38:39]
	s_addk_i32 s11, 0x2000
	s_mov_b32 s62, m0
	s_mov_b32 m0, s11
	s_nop 0
	global_load_lds_dwordx4 v[14:15], off
	s_mov_b32 m0, s62
